# pool<2,4> and conv<2> loops: load batches no longer split by an early vmcnt wait (consumers of the first loads moved behind the last load issue), on top of fold prefetch
# baseline (speedup 1.0000x reference)
; __device__ __forceinline__ float fsigmoid(float v) { return __builtin_amdgcn_rcpf(1.f + __builtin_amdgcn_exp2f(-v * LOG2E)); }
; __device__ __forceinline__ u32x4 pack8(const float (&f)[8]) { u32x4 w; w.x = cvtpk(f[0], f[1]); w.y = cvtpk(f[2], f[3]); w.z = cvtpk(f[4], f[5]); w.w = cvtpk(f[6], f[7]); return w; }
; template <int W, int NI> __device__ __forceinline__ void pool_items(bf16_t* PB, const float* pscale, const int (&rps)[NI], int g, int lane) {
;     const int ch = g * 256 + (lane & 31) * 8;
;     u32x4 v[NI][W], zw[NI]; int t[NI]; bf16_t* zp[NI];
; #pragma unroll
;     for (int q = 0; q < NI; ++q) { const int row = 2 * rps[q] + (lane >> 5); t[q] = row & (SEQ - 1);
;         const bf16_t* xp = PB + (size_t)row * PBW + C_XA + ch;
; #pragma unroll
;         for (int jj = 0; jj < W; ++jj) { const int back = (jj <= t[q]) ? jj : 0; v[q][jj] = *(const u32x4*)(xp - (size_t)back * PBW); }
;         zp[q] = PB + (size_t)row * PBW + C_ZA + ch; zw[q] = *(const u32x4*)zp[q]; }
;     const f32x4 p0 = *(const f32x4*)(pscale + ch), p1 = *(const f32x4*)(pscale + ch + 4);
;     u32x4 outw[NI];
; #pragma unroll
;     for (int q = 0; q < NI; ++q) {
;         float za[8], sum[8], x0[8]; unpack8(zw[q], za); unpack8(v[q][0], x0);
; #pragma unroll
;         for (int e = 0; e < 8; ++e) sum[e] = x0[e];
; #pragma unroll
;         for (int jj = 1; jj < W; ++jj) { float f[8]; unpack8(v[q][jj], f); const float mk = (jj <= t[q]) ? 1.f : 0.f;
; #pragma unroll
;             for (int e = 0; e < 8; ++e) sum[e] += mk * f[e]; }
;         const int cnt = (t[q] + 1 < W) ? (t[q] + 1) : W;
;         const float inv = 1.f / (float)cnt;
;         float y[8];
; #pragma unroll
;         for (int e = 0; e < 8; ++e) { const float ps = (e < 4) ? p0[e & 3] : p1[e & 3]; y[e] = (sum[e] * inv - x0[e]) * ps * (za[e] * fsigmoid(za[e])); }
;         outw[q] = pack8(y); }
.LBB0_371:
	v_add_u32_e32 v0, s13, v57
	v_add_u32_e32 v12, s14, v57
	s_add_i32 s15, s2, s74
	v_and_b32_e32 v4, 0xfff, v0
	v_mad_i64_i32 v[48:49], s[2:3], v0, s65, v[46:47]
	v_and_b32_e32 v13, 0xfff, v12
	v_mad_i64_i32 v[50:51], s[2:3], v12, s65, v[46:47]
	v_cmp_eq_u32_e32 vcc, 0, v4
	v_cmp_eq_u32_e64 s[2:3], 0, v13
	global_load_dwordx4 v[0:3], v[48:49], off
	v_cndmask_b32_e64 v5, -1, 0, vcc
	v_cndmask_b32_e64 v4, v225, 0, vcc
	v_cndmask_b32_e64 v13, -1, 0, s[2:3]
	v_cndmask_b32_e64 v12, v225, 0, s[2:3]
	v_lshl_add_u64 v[4:5], v[48:49], 0, v[4:5]
	v_lshl_add_u64 v[12:13], v[50:51], 0, v[12:13]
	global_load_dwordx4 v[4:7], v[4:5], off
	s_nop 0
	global_load_dwordx4 v[8:11], v[48:49], off offset:2048
	global_load_dwordx4 v[16:19], v[50:51], off
	global_load_dwordx4 v[24:27], v[12:13], off
	global_load_dwordx4 v[32:35], v[50:51], off offset:2048
	v_add_u32_e32 v12, s12, v57
	v_and_b32_e32 v13, 0xfff, v12
	v_mad_i64_i32 v[52:53], s[4:5], v12, s65, v[46:47]
	v_cmp_eq_u32_e64 s[4:5], 0, v13
	global_load_dwordx4 v[62:65], v[52:53], off
	v_cndmask_b32_e64 v13, -1, 0, s[4:5]
	v_cndmask_b32_e64 v12, v225, 0, s[4:5]
	v_lshl_add_u64 v[12:13], v[52:53], 0, v[12:13]
	global_load_dwordx4 v[66:69], v[12:13], off
	global_load_dwordx4 v[70:73], v[52:53], off offset:2048
	v_add_u32_e32 v12, s11, v57
	v_and_b32_e32 v20, 0xfff, v12
	v_mad_i64_i32 v[54:55], s[6:7], v12, s65, v[46:47]
	v_cmp_eq_u32_e64 s[6:7], 0, v20
	global_load_dwordx4 v[12:15], v[54:55], off
	v_cndmask_b32_e64 v76, 1.0, 0, s[4:5]
	v_cndmask_b32_e64 v21, -1, 0, s[6:7]
	v_cndmask_b32_e64 v20, v225, 0, s[6:7]
	v_lshl_add_u64 v[20:21], v[54:55], 0, v[20:21]
	global_load_dwordx4 v[20:23], v[20:21], off
	s_nop 0
	global_load_dwordx4 v[28:31], v[54:55], off offset:2048
	global_load_dwordx4 v[40:43], v[44:45], off
	global_load_dwordx4 v[36:39], v[44:45], off offset:16
	s_waitcnt vmcnt(7)
	v_lshlrev_b32_e32 v78, 16, v65
	v_and_b32_e32 v79, 0xffff0000, v65
	v_cndmask_b32_e64 v74, 0.5, 1.0, s[4:5]
	s_waitcnt vmcnt(5)
	v_lshlrev_b32_e32 v58, 16, v73
	v_mul_f32_e32 v56, 0xbfb8aa3b, v58
	v_exp_f32_e32 v56, v56
	v_and_b32_e32 v59, 0xffff0000, v73
	v_add_f32_e32 v56, 1.0, v56
	v_rcp_f32_e32 v60, v56
	v_mul_f32_e32 v56, 0xbfb8aa3b, v59
	v_exp_f32_e32 v56, v56
	s_waitcnt vmcnt(4)
	v_lshlrev_b32_e32 v82, 16, v14
	v_and_b32_e32 v83, 0xffff0000, v14
	v_add_f32_e32 v56, 1.0, v56
	v_rcp_f32_e32 v61, v56
	v_cndmask_b32_e64 v56, 0.5, 1.0, s[6:7]
	v_pk_mul_f32 v[58:59], v[60:61], v[58:59]
	v_lshlrev_b32_e32 v60, 16, v69
	v_and_b32_e32 v61, 0xffff0000, v69
	v_pk_fma_f32 v[60:61], v[76:77], v[60:61], v[78:79] op_sel_hi:[0,1,1]
	v_pk_fma_f32 v[60:61], v[74:75], v[60:61], v[78:79] op_sel_hi:[0,1,1] neg_lo:[0,0,1] neg_hi:[0,0,1]
	s_waitcnt vmcnt(0)
	v_pk_mul_f32 v[60:61], v[60:61], v[38:39]
	v_and_b32_e32 v69, 0xffff0000, v64
	v_pk_mul_f32 v[78:79], v[60:61], v[58:59]
	v_lshlrev_b32_e32 v60, 16, v30
	v_and_b32_e32 v61, 0xffff0000, v30
	v_mul_f32_e32 v30, 0xbfb8aa3b, v60
	v_exp_f32_e32 v30, v30
	v_cndmask_b32_e64 v58, 1.0, 0, s[6:7]
	v_add_f32_e32 v30, 1.0, v30
	v_rcp_f32_e32 v80, v30
	v_mul_f32_e32 v30, 0xbfb8aa3b, v61
	v_exp_f32_e32 v30, v30
	s_nop 0
	v_add_f32_e32 v30, 1.0, v30
	v_rcp_f32_e32 v81, v30
	s_nop 0
	v_pk_mul_f32 v[60:61], v[80:81], v[60:61]
	v_lshlrev_b32_e32 v80, 16, v22
	v_and_b32_e32 v81, 0xffff0000, v22
	v_pk_fma_f32 v[80:81], v[58:59], v[80:81], v[82:83] op_sel_hi:[0,1,1]
	v_pk_fma_f32 v[80:81], v[56:57], v[80:81], v[82:83] op_sel_hi:[0,1,1] neg_lo:[0,0,1] neg_hi:[0,0,1]
	v_pk_mul_f32 v[80:81], v[36:37], v[80:81]
	v_lshlrev_b32_e32 v82, 16, v63
	v_pk_mul_f32 v[60:61], v[80:81], v[60:61]
	v_lshlrev_b32_e32 v80, 16, v72
	v_mul_f32_e32 v14, 0xbfb8aa3b, v80
	v_exp_f32_e32 v14, v14
	v_and_b32_e32 v81, 0xffff0000, v72
	v_and_b32_e32 v83, 0xffff0000, v63
	v_add_f32_e32 v14, 1.0, v14
	v_rcp_f32_e32 v72, v14
	v_mul_f32_e32 v14, 0xbfb8aa3b, v81
	v_exp_f32_e32 v14, v14
	s_nop 0
	v_add_f32_e32 v14, 1.0, v14
	v_rcp_f32_e32 v73, v14
	s_nop 0
	v_pk_mul_f32 v[72:73], v[72:73], v[80:81]
	v_lshlrev_b32_e32 v80, 16, v68
	v_and_b32_e32 v81, 0xffff0000, v68
	v_lshlrev_b32_e32 v68, 16, v64
	v_pk_fma_f32 v[64:65], v[76:77], v[80:81], v[68:69] op_sel_hi:[0,1,1]
	v_pk_fma_f32 v[64:65], v[74:75], v[64:65], v[68:69] op_sel_hi:[0,1,1] neg_lo:[0,0,1] neg_hi:[0,0,1]
	v_lshlrev_b32_e32 v68, 16, v29
	v_mul_f32_e32 v14, 0xbfb8aa3b, v68
	v_exp_f32_e32 v14, v14
	v_pk_mul_f32 v[64:65], v[64:65], v[36:37]
	v_and_b32_e32 v69, 0xffff0000, v29
	v_pk_mul_f32 v[64:65], v[64:65], v[72:73]
	v_add_f32_e32 v14, 1.0, v14
	v_rcp_f32_e32 v72, v14
	v_mul_f32_e32 v14, 0xbfb8aa3b, v69
	v_exp_f32_e32 v14, v14
	v_lshlrev_b32_e32 v80, 16, v13
	v_and_b32_e32 v81, 0xffff0000, v13
	v_cvt_pk_bf16_f32 v64, v64, v65
	v_add_f32_e32 v14, 1.0, v14
	v_rcp_f32_e32 v73, v14
	v_cvt_pk_bf16_f32 v65, v78, v79
	v_pk_mul_f32 v[68:69], v[72:73], v[68:69]
	v_lshlrev_b32_e32 v72, 16, v21
	v_and_b32_e32 v73, 0xffff0000, v21
	v_pk_fma_f32 v[72:73], v[58:59], v[72:73], v[80:81] op_sel_hi:[0,1,1]
	v_pk_fma_f32 v[72:73], v[56:57], v[72:73], v[80:81] op_sel_hi:[0,1,1] neg_lo:[0,0,1] neg_hi:[0,0,1]
	v_pk_mul_f32 v[72:73], v[42:43], v[72:73]
	v_and_b32_e32 v21, 0xffff0000, v12
	v_pk_mul_f32 v[68:69], v[72:73], v[68:69]
	v_lshlrev_b32_e32 v72, 16, v71
	v_mul_f32_e32 v13, 0xbfb8aa3b, v72
	v_exp_f32_e32 v13, v13
	v_and_b32_e32 v73, 0xffff0000, v71
	v_and_b32_e32 v71, 0xffff0000, v19
	v_add_f32_e32 v13, 1.0, v13
	v_rcp_f32_e32 v80, v13
	v_mul_f32_e32 v13, 0xbfb8aa3b, v73
	v_exp_f32_e32 v13, v13
	s_nop 0
	v_add_f32_e32 v13, 1.0, v13
	v_rcp_f32_e32 v81, v13
	s_nop 0
	v_pk_mul_f32 v[72:73], v[80:81], v[72:73]
	v_lshlrev_b32_e32 v80, 16, v67
	v_and_b32_e32 v81, 0xffff0000, v67
; __device__ __forceinline__ float fsigmoid(float v) { return __builtin_amdgcn_rcpf(1.f + __builtin_amdgcn_exp2f(-v * LOG2E)); }
; __device__ __forceinline__ u32x4 pack8(const float (&f)[8]) { u32x4 w; w.x = cvtpk(f[0], f[1]); w.y = cvtpk(f[2], f[3]); w.z = cvtpk(f[4], f[5]); w.w = cvtpk(f[6], f[7]); return w; }
; template <int W, int NI> __device__ __forceinline__ void pool_items(bf16_t* PB, const float* pscale, const int (&rps)[NI], int g, int lane) {
;     ...
;     for (int q = 0; q < NI; ++q) {
;         float za[8], sum[8], x0[8]; unpack8(zw[q], za); unpack8(v[q][0], x0);
; #pragma unroll
;         for (int e = 0; e < 8; ++e) sum[e] = x0[e];
; #pragma unroll
;         for (int jj = 1; jj < W; ++jj) { float f[8]; unpack8(v[q][jj], f); const float mk = (jj <= t[q]) ? 1.f : 0.f;
; #pragma unroll
;             for (int e = 0; e < 8; ++e) sum[e] += mk * f[e]; }
;         const int cnt = (t[q] + 1 < W) ? (t[q] + 1) : W;
;         const float inv = 1.f / (float)cnt;
;         float y[8];
; #pragma unroll
;         for (int e = 0; e < 8; ++e) { const float ps = (e < 4) ? p0[e & 3] : p1[e & 3]; y[e] = (sum[e] * inv - x0[e]) * ps * (za[e] * fsigmoid(za[e])); }
;         outw[q] = pack8(y); }
	v_pk_fma_f32 v[80:81], v[76:77], v[80:81], v[82:83] op_sel_hi:[0,1,1]
	v_pk_fma_f32 v[80:81], v[74:75], v[80:81], v[82:83] op_sel_hi:[0,1,1] neg_lo:[0,0,1] neg_hi:[0,0,1]
	v_pk_mul_f32 v[80:81], v[42:43], v[80:81]
	v_and_b32_e32 v67, 0xffff0000, v62
	v_pk_mul_f32 v[72:73], v[80:81], v[72:73]
	v_lshlrev_b32_e32 v80, 16, v28
	v_mul_f32_e32 v13, 0xbfb8aa3b, v80
	v_exp_f32_e32 v13, v13
	v_and_b32_e32 v81, 0xffff0000, v28
	v_cvt_pk_bf16_f32 v63, v72, v73
	v_add_f32_e32 v13, 1.0, v13
	v_rcp_f32_e32 v28, v13
	v_mul_f32_e32 v13, 0xbfb8aa3b, v81
	v_exp_f32_e32 v13, v13
	s_nop 0
	v_add_f32_e32 v13, 1.0, v13
	v_rcp_f32_e32 v29, v13
	s_nop 0
	v_pk_mul_f32 v[28:29], v[28:29], v[80:81]
	v_lshlrev_b32_e32 v80, 16, v20
	v_and_b32_e32 v81, 0xffff0000, v20
	v_lshlrev_b32_e32 v20, 16, v12
	v_pk_fma_f32 v[12:13], v[58:59], v[80:81], v[20:21] op_sel_hi:[0,1,1]
	v_pk_fma_f32 v[12:13], v[56:57], v[12:13], v[20:21] op_sel_hi:[0,1,1] neg_lo:[0,0,1] neg_hi:[0,0,1]
	v_lshlrev_b32_e32 v20, 16, v70
	v_mul_f32_e32 v14, 0xbfb8aa3b, v20
	v_exp_f32_e32 v14, v14
	v_pk_mul_f32 v[12:13], v[40:41], v[12:13]
	v_and_b32_e32 v21, 0xffff0000, v70
	v_pk_mul_f32 v[12:13], v[12:13], v[28:29]
	v_add_f32_e32 v14, 1.0, v14
	v_rcp_f32_e32 v28, v14
	v_mul_f32_e32 v14, 0xbfb8aa3b, v21
	v_exp_f32_e32 v14, v14
	v_lshlrev_b32_e32 v70, 16, v19
	v_add_f32_e32 v14, 1.0, v14
	v_rcp_f32_e32 v29, v14
	v_cndmask_b32_e64 v14, 0.5, 1.0, s[2:3]
	v_pk_mul_f32 v[20:21], v[28:29], v[20:21]
	v_lshlrev_b32_e32 v28, 16, v66
	v_and_b32_e32 v29, 0xffff0000, v66
	v_lshlrev_b32_e32 v66, 16, v62
	v_pk_fma_f32 v[28:29], v[76:77], v[28:29], v[66:67] op_sel_hi:[0,1,1]
	v_pk_fma_f32 v[28:29], v[74:75], v[28:29], v[66:67] op_sel_hi:[0,1,1] neg_lo:[0,0,1] neg_hi:[0,0,1]
	v_pk_mul_f32 v[28:29], v[40:41], v[28:29]
	s_nop 0
	v_pk_mul_f32 v[20:21], v[28:29], v[20:21]
	v_lshlrev_b32_e32 v28, 16, v35
	v_cvt_pk_bf16_f32 v62, v20, v21
	v_mul_f32_e32 v21, 0xbfb8aa3b, v28
	v_exp_f32_e32 v21, v21
	v_and_b32_e32 v29, 0xffff0000, v35
	v_cndmask_b32_e64 v20, 1.0, 0, s[2:3]
	s_add_i32 s2, s15, s31
	v_add_f32_e32 v21, 1.0, v21
	v_rcp_f32_e32 v66, v21
	v_mul_f32_e32 v21, 0xbfb8aa3b, v29
	v_exp_f32_e32 v21, v21
	s_add_i32 s3, s31, s2
	s_cmpk_gt_i32 s3, 0x1fff
	v_add_f32_e32 v21, 1.0, v21
	v_rcp_f32_e32 v67, v21
	s_nop 0
	v_pk_mul_f32 v[28:29], v[66:67], v[28:29]
	v_lshlrev_b32_e32 v66, 16, v27
	v_and_b32_e32 v67, 0xffff0000, v27
	v_pk_fma_f32 v[66:67], v[20:21], v[66:67], v[70:71] op_sel_hi:[0,1,1]
	v_pk_fma_f32 v[66:67], v[14:15], v[66:67], v[70:71] op_sel_hi:[0,1,1] neg_lo:[0,0,1] neg_hi:[0,0,1]
	v_pk_mul_f32 v[66:67], v[66:67], v[38:39]
	v_and_b32_e32 v27, 0xffff0000, v18
	v_pk_mul_f32 v[28:29], v[28:29], v[66:67]
	v_lshlrev_b32_e32 v66, 16, v34
	v_mul_f32_e32 v19, 0xbfb8aa3b, v66
	v_exp_f32_e32 v19, v19
	v_and_b32_e32 v67, 0xffff0000, v34
	v_add_f32_e32 v19, 1.0, v19
	v_rcp_f32_e32 v34, v19
	v_mul_f32_e32 v19, 0xbfb8aa3b, v67
	v_exp_f32_e32 v19, v19
	s_nop 0
	v_add_f32_e32 v19, 1.0, v19
	v_rcp_f32_e32 v35, v19
	s_nop 0
	v_pk_mul_f32 v[34:35], v[34:35], v[66:67]
	v_lshlrev_b32_e32 v66, 16, v26
	v_and_b32_e32 v67, 0xffff0000, v26
	v_lshlrev_b32_e32 v26, 16, v18
	v_pk_fma_f32 v[18:19], v[20:21], v[66:67], v[26:27] op_sel_hi:[0,1,1]
	v_pk_fma_f32 v[18:19], v[14:15], v[18:19], v[26:27] op_sel_hi:[0,1,1] neg_lo:[0,0,1] neg_hi:[0,0,1]
	v_lshlrev_b32_e32 v26, 16, v33
	v_mul_f32_e32 v21, 0xbfb8aa3b, v26
	v_exp_f32_e32 v21, v21
	v_pk_mul_f32 v[18:19], v[18:19], v[36:37]
	v_and_b32_e32 v27, 0xffff0000, v33
	v_pk_mul_f32 v[18:19], v[34:35], v[18:19]
	v_add_f32_e32 v21, 1.0, v21
	v_rcp_f32_e32 v34, v21
	v_mul_f32_e32 v21, 0xbfb8aa3b, v27
	v_exp_f32_e32 v21, v21
	v_lshlrev_b32_e32 v66, 16, v17
	v_and_b32_e32 v67, 0xffff0000, v17
	v_cvt_pk_bf16_f32 v18, v18, v19
	v_add_f32_e32 v21, 1.0, v21
	v_rcp_f32_e32 v35, v21
	v_cvt_pk_bf16_f32 v19, v28, v29
	v_lshlrev_b32_e32 v28, 16, v3
	v_and_b32_e32 v29, 0xffff0000, v3
	v_pk_mul_f32 v[26:27], v[34:35], v[26:27]
	v_lshlrev_b32_e32 v34, 16, v25
	v_and_b32_e32 v35, 0xffff0000, v25
	v_pk_fma_f32 v[34:35], v[20:21], v[34:35], v[66:67] op_sel_hi:[0,1,1]
	v_pk_fma_f32 v[34:35], v[14:15], v[34:35], v[66:67] op_sel_hi:[0,1,1] neg_lo:[0,0,1] neg_hi:[0,0,1]
	v_pk_mul_f32 v[34:35], v[34:35], v[42:43]
	v_and_b32_e32 v25, 0xffff0000, v16
	v_pk_mul_f32 v[26:27], v[26:27], v[34:35]
	v_lshlrev_b32_e32 v34, 16, v32
	v_mul_f32_e32 v17, 0xbfb8aa3b, v34
	v_exp_f32_e32 v17, v17
	v_and_b32_e32 v35, 0xffff0000, v32
	v_add_f32_e32 v17, 1.0, v17
	v_rcp_f32_e32 v32, v17
	v_mul_f32_e32 v17, 0xbfb8aa3b, v35
	v_exp_f32_e32 v17, v17
	s_nop 0
	v_add_f32_e32 v17, 1.0, v17
	v_rcp_f32_e32 v33, v17
; __device__ __forceinline__ float fsigmoid(float v) { return __builtin_amdgcn_rcpf(1.f + __builtin_amdgcn_exp2f(-v * LOG2E)); }
; __device__ __forceinline__ u32x4 pack8(const float (&f)[8]) { u32x4 w; w.x = cvtpk(f[0], f[1]); w.y = cvtpk(f[2], f[3]); w.z = cvtpk(f[4], f[5]); w.w = cvtpk(f[6], f[7]); return w; }
; template <int W, int NI> __device__ __forceinline__ void pool_items(bf16_t* PB, const float* pscale, const int (&rps)[NI], int g, int lane) {
;     ...
;     for (int q = 0; q < NI; ++q) {
;         float za[8], sum[8], x0[8]; unpack8(zw[q], za); unpack8(v[q][0], x0);
; #pragma unroll
;         for (int e = 0; e < 8; ++e) sum[e] = x0[e];
; #pragma unroll
;         for (int jj = 1; jj < W; ++jj) { float f[8]; unpack8(v[q][jj], f); const float mk = (jj <= t[q]) ? 1.f : 0.f;
; #pragma unroll
;             for (int e = 0; e < 8; ++e) sum[e] += mk * f[e]; }
;         const int cnt = (t[q] + 1 < W) ? (t[q] + 1) : W;
;         const float inv = 1.f / (float)cnt;
;         float y[8];
; #pragma unroll
;         for (int e = 0; e < 8; ++e) { const float ps = (e < 4) ? p0[e & 3] : p1[e & 3]; y[e] = (sum[e] * inv - x0[e]) * ps * (za[e] * fsigmoid(za[e])); }
;         outw[q] = pack8(y); }
; #pragma unroll
;     for (int q = 0; q < NI; ++q) *(u32x4*)zp[q] = outw[q];
	s_nop 0
	v_pk_mul_f32 v[32:33], v[32:33], v[34:35]
	v_lshlrev_b32_e32 v34, 16, v24
	v_and_b32_e32 v35, 0xffff0000, v24
	v_lshlrev_b32_e32 v24, 16, v16
	v_pk_fma_f32 v[16:17], v[20:21], v[34:35], v[24:25] op_sel_hi:[0,1,1]
	v_pk_fma_f32 v[16:17], v[14:15], v[16:17], v[24:25] op_sel_hi:[0,1,1] neg_lo:[0,0,1] neg_hi:[0,0,1]
	v_lshlrev_b32_e32 v24, 16, v11
	v_and_b32_e32 v25, 0xffff0000, v11
	v_mul_f32_e32 v11, 0xbfb8aa3b, v24
	v_exp_f32_e32 v11, v11
	v_pk_mul_f32 v[16:17], v[16:17], v[40:41]
	v_cndmask_b32_e64 v20, 1.0, 0, vcc
	v_pk_mul_f32 v[16:17], v[32:33], v[16:17]
	v_add_f32_e32 v11, 1.0, v11
	v_cvt_pk_bf16_f32 v16, v16, v17
	v_cvt_pk_bf16_f32 v17, v26, v27
	v_rcp_f32_e32 v26, v11
	v_mul_f32_e32 v11, 0xbfb8aa3b, v25
	v_exp_f32_e32 v11, v11
	v_cndmask_b32_e64 v14, 0.5, 1.0, vcc
	v_add_f32_e32 v11, 1.0, v11
	v_rcp_f32_e32 v27, v11
	s_nop 0
	v_pk_mul_f32 v[24:25], v[26:27], v[24:25]
	v_lshlrev_b32_e32 v26, 16, v7
	v_and_b32_e32 v27, 0xffff0000, v7
	v_pk_fma_f32 v[26:27], v[20:21], v[26:27], v[28:29] op_sel_hi:[0,1,1]
	v_pk_fma_f32 v[26:27], v[14:15], v[26:27], v[28:29] op_sel_hi:[0,1,1] neg_lo:[0,0,1] neg_hi:[0,0,1]
	v_pk_mul_f32 v[26:27], v[26:27], v[38:39]
	v_and_b32_e32 v7, 0xffff0000, v2
	v_pk_mul_f32 v[24:25], v[24:25], v[26:27]
	v_lshlrev_b32_e32 v26, 16, v10
	v_mul_f32_e32 v3, 0xbfb8aa3b, v26
	v_exp_f32_e32 v3, v3
	v_and_b32_e32 v27, 0xffff0000, v10
	v_add_f32_e32 v3, 1.0, v3
	v_rcp_f32_e32 v10, v3
	v_mul_f32_e32 v3, 0xbfb8aa3b, v27
	v_exp_f32_e32 v3, v3
	s_nop 0
	v_add_f32_e32 v3, 1.0, v3
	v_rcp_f32_e32 v11, v3
	s_nop 0
	v_pk_mul_f32 v[10:11], v[10:11], v[26:27]
	v_lshlrev_b32_e32 v26, 16, v6
	v_and_b32_e32 v27, 0xffff0000, v6
	v_lshlrev_b32_e32 v6, 16, v2
	v_pk_fma_f32 v[2:3], v[20:21], v[26:27], v[6:7] op_sel_hi:[0,1,1]
	v_pk_fma_f32 v[2:3], v[14:15], v[2:3], v[6:7] op_sel_hi:[0,1,1] neg_lo:[0,0,1] neg_hi:[0,0,1]
	v_lshlrev_b32_e32 v6, 16, v9
	v_and_b32_e32 v7, 0xffff0000, v9
	v_mul_f32_e32 v9, 0xbfb8aa3b, v6
	v_exp_f32_e32 v9, v9
	v_pk_mul_f32 v[2:3], v[2:3], v[36:37]
	v_lshlrev_b32_e32 v26, 16, v1
	v_pk_mul_f32 v[2:3], v[10:11], v[2:3]
	v_add_f32_e32 v9, 1.0, v9
	v_rcp_f32_e32 v10, v9
	v_mul_f32_e32 v9, 0xbfb8aa3b, v7
	v_exp_f32_e32 v9, v9
	v_and_b32_e32 v27, 0xffff0000, v1
	v_cvt_pk_bf16_f32 v2, v2, v3
	v_cvt_pk_bf16_f32 v3, v24, v25
	v_add_f32_e32 v9, 1.0, v9
	v_rcp_f32_e32 v11, v9
	s_nop 0
	v_pk_mul_f32 v[6:7], v[10:11], v[6:7]
	v_lshlrev_b32_e32 v10, 16, v5
	v_and_b32_e32 v11, 0xffff0000, v5
	v_pk_fma_f32 v[10:11], v[20:21], v[10:11], v[26:27] op_sel_hi:[0,1,1]
	v_pk_fma_f32 v[10:11], v[14:15], v[10:11], v[26:27] op_sel_hi:[0,1,1] neg_lo:[0,0,1] neg_hi:[0,0,1]
	v_pk_mul_f32 v[10:11], v[10:11], v[42:43]
	v_and_b32_e32 v5, 0xffff0000, v0
	v_pk_mul_f32 v[6:7], v[6:7], v[10:11]
	v_lshlrev_b32_e32 v10, 16, v8
	v_mul_f32_e32 v1, 0xbfb8aa3b, v10
	v_exp_f32_e32 v1, v1
	v_and_b32_e32 v11, 0xffff0000, v8
	v_add_f32_e32 v1, 1.0, v1
	v_rcp_f32_e32 v8, v1
	v_mul_f32_e32 v1, 0xbfb8aa3b, v11
	v_exp_f32_e32 v1, v1
	s_nop 0
	v_add_f32_e32 v1, 1.0, v1
	v_rcp_f32_e32 v9, v1
	s_nop 0
	v_pk_mul_f32 v[8:9], v[8:9], v[10:11]
	v_lshlrev_b32_e32 v10, 16, v4
	v_and_b32_e32 v11, 0xffff0000, v4
	v_lshlrev_b32_e32 v4, 16, v0
	v_pk_fma_f32 v[0:1], v[20:21], v[10:11], v[4:5] op_sel_hi:[0,1,1]
	v_pk_fma_f32 v[0:1], v[14:15], v[0:1], v[4:5] op_sel_hi:[0,1,1] neg_lo:[0,0,1] neg_hi:[0,0,1]
	v_pk_mul_f32 v[0:1], v[0:1], v[40:41]
	v_lshlrev_b32_e32 v4, 16, v31
	v_pk_mul_f32 v[0:1], v[8:9], v[0:1]
	v_and_b32_e32 v5, 0xffff0000, v31
	v_cvt_pk_bf16_f32 v0, v0, v1
	v_cvt_pk_bf16_f32 v1, v6, v7
	v_mul_f32_e32 v6, 0xbfb8aa3b, v4
	v_mul_f32_e32 v7, 0xbfb8aa3b, v5
	v_exp_f32_e32 v6, v6
	v_exp_f32_e32 v7, v7
	v_lshlrev_b32_e32 v8, 16, v15
	v_and_b32_e32 v9, 0xffff0000, v15
	v_add_f32_e32 v6, 1.0, v6
	v_add_f32_e32 v7, 1.0, v7
	v_rcp_f32_e32 v6, v6
	v_rcp_f32_e32 v7, v7
	v_lshlrev_b32_e32 v10, 16, v23
	v_and_b32_e32 v11, 0xffff0000, v23
	v_pk_fma_f32 v[10:11], v[58:59], v[10:11], v[8:9] op_sel_hi:[0,1,1]
	v_pk_fma_f32 v[8:9], v[56:57], v[10:11], v[8:9] op_sel_hi:[0,1,1] neg_lo:[0,0,1] neg_hi:[0,0,1]
	v_pk_mul_f32 v[8:9], v[38:39], v[8:9]
	v_pk_mul_f32 v[4:5], v[6:7], v[4:5]
	v_add_u32_e32 v57, s91, v57
	v_pk_mul_f32 v[8:9], v[8:9], v[4:5]
	v_cvt_pk_bf16_f32 v4, v12, v13
	v_cvt_pk_bf16_f32 v5, v68, v69
	v_cvt_pk_bf16_f32 v6, v60, v61
	v_cvt_pk_bf16_f32 v7, v8, v9
	global_store_dwordx4 v[48:49], v[0:3], off offset:2048
	global_store_dwordx4 v[50:51], v[16:19], off offset:2048
	global_store_dwordx4 v[52:53], v[62:65], off offset:2048
	global_store_dwordx4 v[54:55], v[4:7], off offset:2048
	s_cbranch_scc0 .LBB0_371

; template <int NI> __device__ __forceinline__ void conv_items(bf16_t* PB, const float* cw, const int (&items)[NI], int lane) {
;     u32x4 uw[NI][3], cgw[NI][3], bgw[NI], zcw[NI]; f32x4 w0[NI][3], w1[NI][3]; int t[NI]; bf16_t* zp[NI];
; #pragma unroll
;     for (int q = 0; q < NI; ++q) { const int row = items[q] >> 1, ch = (items[q] & 1) * 512 + lane * 8; t[q] = row & (SEQ - 1);
;         const bf16_t* base = PB + (size_t)row * PBW + ch;
; #pragma unroll
;         for (int dt = 0; dt < 3; ++dt) { const int back = (dt <= t[q]) ? dt : 0;
;             uw[q][dt] = *(const u32x4*)(base - (size_t)back * PBW + C_U); cgw[q][dt] = *(const u32x4*)(base - (size_t)back * PBW + C_CG);
;             w0[q][dt] = *(const f32x4*)(cw + (2 - dt) * 1024 + ch); w1[q][dt] = *(const f32x4*)(cw + (2 - dt) * 1024 + ch + 4); }
;         zp[q] = PB + (size_t)row * PBW + C_ZC + ch;
;         bgw[q] = *(const u32x4*)(base + C_BG); zcw[q] = *(const u32x4*)zp[q]; }
;     u32x4 outw[NI];
; #pragma unroll
;     for (int q = 0; q < NI; ++q) {
;         float y[8];
; #pragma unroll
;         for (int e = 0; e < 8; ++e) y[e] = 0.f;
; #pragma unroll
;         for (int dt = 0; dt < 3; ++dt) { float u[8], c[8]; unpack8(uw[q][dt], u); unpack8(cgw[q][dt], c); const float mk = (dt <= t[q]) ? 1.f : 0.f;
; #pragma unroll
;             for (int e = 0; e < 8; ++e) { const float wv = (e < 4) ? w0[q][dt][e & 3] : w1[q][dt][e & 3]; y[e] += (mk * wv) * (c[e] * u[e]); } }
.LBB0_397:
	s_and_b32 s5, s6, 0x200
	v_add_u32_e32 v0, s5, v163
	s_add_i32 s4, s81, s95
	v_ashrrev_i32_e32 v1, 31, v0
	s_ashr_i32 s4, s4, 1
	v_lshlrev_b64 v[24:25], 1, v[0:1]
	v_lshl_add_u64 v[0:1], v[0:1], 2, s[2:3]
	s_and_b32 s7, s4, 0xfff
	s_mul_hi_i32 s5, s4, 0x9000
	s_mul_i32 s4, s4, 0x9000
	v_add_co_u32_e32 v4, vcc, s52, v0
	s_add_u32 s4, s92, s4
	s_nop 0
	v_addc_co_u32_e32 v5, vcc, 0, v1, vcc
	s_addc_u32 s5, s93, s5
	v_add_co_u32_e32 v10, vcc, s1, v0
	v_lshl_add_u64 v[26:27], s[4:5], 0, v[24:25]
	s_nop 0
	v_addc_co_u32_e32 v11, vcc, 0, v1, vcc
	s_cmp_eq_u32 s7, 0
	v_add_co_u32_e32 v28, vcc, s33, v26
	s_cselect_b64 s[4:5], -1, 0
	s_nop 0
	v_addc_co_u32_e32 v29, vcc, 0, v27, vcc
	v_add_co_u32_e32 v80, vcc, s90, v26
	v_cndmask_b32_e64 v84, 1.0, 0, s[4:5]
	s_and_b64 s[4:5], s[4:5], exec
	v_lshl_add_u64 v[2:3], v[0:1], 0, s[38:39]
	v_lshl_add_u64 v[8:9], v[0:1], 0, s[40:41]
	v_addc_co_u32_e32 v81, vcc, 0, v27, vcc
	s_cselect_b32 s5, 0, -1
	s_cselect_b32 s4, 0, 0xffff7000
	s_cmp_lt_u32 s7, 2
	global_load_dwordx4 v[16:19], v[0:1], off offset:16
	global_load_dwordx4 v[20:23], v[0:1], off
	s_nop 0
	global_load_dwordx4 v[4:7], v[4:5], off
	s_nop 0
	global_load_dwordx4 v[0:3], v[2:3], off offset:16
	s_nop 0
	global_load_dwordx4 v[12:15], v[10:11], off
	s_nop 0
	global_load_dwordx4 v[8:11], v[8:9], off offset:16
	global_load_dwordx4 v[56:59], v[80:81], off offset:-4096
	global_load_dwordx4 v[60:63], v[28:29], off offset:2048
	global_load_dwordx4 v[68:71], v[80:81], off
	global_load_dwordx4 v[76:79], v[80:81], off offset:2048
	v_lshl_add_u64 v[28:29], v[26:27], 0, s[4:5]
	s_cselect_b64 s[4:5], -1, 0
	v_cndmask_b32_e64 v86, 1.0, 0, s[4:5]
	s_and_b64 s[4:5], s[4:5], exec
	s_cselect_b32 s5, 0, -1
	s_cselect_b32 s4, 0, 0xfffee000
	s_ashr_i32 s7, s76, 1
	v_add_co_u32_e32 v28, vcc, s90, v28
	v_lshl_add_u64 v[26:27], v[26:27], 0, s[4:5]
	s_and_b32 s8, s7, 0xfff
	s_mul_hi_i32 s5, s7, 0x9000
	s_mul_i32 s7, s7, 0x9000
	v_addc_co_u32_e32 v29, vcc, 0, v29, vcc
	s_add_u32 s4, s92, s7
	global_load_dwordx4 v[64:67], v[28:29], off offset:-4096
	global_load_dwordx4 v[72:75], v[28:29], off
	v_add_co_u32_e32 v26, vcc, s90, v26
	s_addc_u32 s5, s93, s5
	s_nop 0
	v_addc_co_u32_e32 v27, vcc, 0, v27, vcc
	v_lshl_add_u64 v[92:93], s[4:5], 0, v[24:25]
	s_cmp_eq_u32 s8, 0
	v_add_co_u32_e32 v24, vcc, s33, v92
	s_cselect_b64 s[4:5], -1, 0
	s_nop 0
	v_addc_co_u32_e32 v25, vcc, 0, v93, vcc
	global_load_dwordx4 v[48:51], v[26:27], off offset:-4096
	global_load_dwordx4 v[52:55], v[26:27], off
	v_add_co_u32_e32 v82, vcc, s90, v92
	v_cndmask_b32_e64 v88, 1.0, 0, s[4:5]
	s_and_b64 s[4:5], s[4:5], exec
	v_addc_co_u32_e32 v83, vcc, 0, v93, vcc
	s_cselect_b32 s5, 0, -1
	s_cselect_b32 s4, 0, 0xffff7000
	global_load_dwordx4 v[36:39], v[82:83], off offset:-4096
	global_load_dwordx4 v[44:47], v[82:83], off
	global_load_dwordx4 v[40:43], v[24:25], off offset:2048
	s_cmp_lt_u32 s8, 2
	v_lshl_add_u64 v[24:25], v[92:93], 0, s[4:5]
	s_cselect_b64 s[4:5], -1, 0
	v_add_co_u32_e32 v28, vcc, s90, v24
	v_cndmask_b32_e64 v90, 1.0, 0, s[4:5]
	s_nop 0
	v_addc_co_u32_e32 v29, vcc, 0, v25, vcc
	s_and_b64 s[4:5], s[4:5], exec
	global_load_dwordx4 v[24:27], v[28:29], off
	s_cselect_b32 s5, 0, -1
	s_cselect_b32 s4, 0, 0xfffee000
	global_load_dwordx4 v[32:35], v[28:29], off offset:-4096
	s_nop 0
	global_load_dwordx4 v[28:31], v[82:83], off offset:2048
	v_lshl_add_u64 v[92:93], v[92:93], 0, s[4:5]
	v_add_co_u32_e32 v96, vcc, s90, v92
	s_nop 0
	s_nop 0
	v_addc_co_u32_e32 v97, vcc, 0, v93, vcc
	global_load_dwordx4 v[92:95], v[96:97], off offset:-4096
	s_nop 0
	global_load_dwordx4 v[96:99], v[96:97], off
	s_waitcnt vmcnt(16)
	v_pk_mul_f32 v[106:107], v[84:85], v[14:15] op_sel_hi:[0,1]
	v_pk_mul_f32 v[100:101], v[86:87], v[20:21] op_sel_hi:[0,1]
	v_pk_mul_f32 v[102:103], v[86:87], v[22:23] op_sel_hi:[0,1]
	v_pk_mul_f32 v[104:105], v[86:87], v[16:17] op_sel_hi:[0,1]
	v_pk_mul_f32 v[86:87], v[86:87], v[18:19] op_sel_hi:[0,1]
	v_pk_mul_f32 v[20:21], v[90:91], v[20:21] op_sel_hi:[0,1]
	v_pk_mul_f32 v[22:23], v[90:91], v[22:23] op_sel_hi:[0,1]
	v_pk_mul_f32 v[16:17], v[90:91], v[16:17] op_sel_hi:[0,1]
	v_pk_mul_f32 v[18:19], v[90:91], v[18:19] op_sel_hi:[0,1]
	v_pk_mul_f32 v[90:91], v[84:85], v[12:13] op_sel_hi:[0,1]
	s_waitcnt vmcnt(16)
	v_pk_mul_f32 v[108:109], v[84:85], v[8:9] op_sel_hi:[0,1]
	v_pk_mul_f32 v[84:85], v[84:85], v[10:11] op_sel_hi:[0,1]
	v_pk_mul_f32 v[12:13], v[88:89], v[12:13] op_sel_hi:[0,1]
	v_pk_mul_f32 v[14:15], v[88:89], v[14:15] op_sel_hi:[0,1]
	v_pk_mul_f32 v[8:9], v[88:89], v[8:9] op_sel_hi:[0,1]
	v_pk_mul_f32 v[10:11], v[88:89], v[10:11] op_sel_hi:[0,1]
	s_add_i32 s75, s75, s82
	s_add_i32 s95, s95, s82
	s_add_i32 s6, s6, s9
	s_waitcnt vmcnt(14)
	v_lshlrev_b32_e32 v114, 16, v60
	s_waitcnt vmcnt(13)
	v_lshlrev_b32_e32 v110, 16, v68
	s_waitcnt vmcnt(12)
	v_lshlrev_b32_e32 v88, 16, v76
	v_and_b32_e32 v89, 0xffff0000, v76
	v_and_b32_e32 v111, 0xffff0000, v68
	v_lshlrev_b32_e32 v112, 16, v56
	v_and_b32_e32 v113, 0xffff0000, v56
	v_lshlrev_b32_e32 v76, 16, v77
	v_and_b32_e32 v77, 0xffff0000, v77
	v_lshlrev_b32_e32 v68, 16, v69
	v_and_b32_e32 v69, 0xffff0000, v69
	v_lshlrev_b32_e32 v56, 16, v57
	v_and_b32_e32 v57, 0xffff0000, v57
	v_lshlrev_b32_e32 v116, 16, v78
	v_and_b32_e32 v117, 0xffff0000, v78
	v_lshlrev_b32_e32 v118, 16, v70
	v_and_b32_e32 v119, 0xffff0000, v70
	v_lshlrev_b32_e32 v120, 16, v58
	v_and_b32_e32 v121, 0xffff0000, v58
	v_lshlrev_b32_e32 v78, 16, v79
	v_and_b32_e32 v79, 0xffff0000, v79
	v_mul_f32_e32 v124, 0xbfb8aa3b, v88
	v_pk_mul_f32 v[110:111], v[112:113], v[110:111]
	v_mul_f32_e32 v112, 0xbfb8aa3b, v89
	v_mul_f32_e32 v113, 0xbfb8aa3b, v76
	v_pk_mul_f32 v[56:57], v[56:57], v[68:69]
	v_mul_f32_e32 v125, 0xbfb8aa3b, v77
	v_mul_f32_e32 v126, 0xbfb8aa3b, v116
	v_pk_mul_f32 v[68:69], v[120:121], v[118:119]
	v_mul_f32_e32 v118, 0xbfb8aa3b, v117
	v_mul_f32_e32 v119, 0xbfb8aa3b, v79
	v_mul_f32_e32 v120, 0xbfb8aa3b, v78
	v_exp_f32_e32 v124, v124
	v_exp_f32_e32 v127, v112
	v_exp_f32_e32 v128, v113
	v_exp_f32_e32 v125, v125
	v_exp_f32_e32 v126, v126
	v_exp_f32_e32 v129, v118
	v_exp_f32_e32 v130, v119
	v_exp_f32_e32 v131, v120
	v_lshlrev_b32_e32 v70, 16, v71
	v_and_b32_e32 v71, 0xffff0000, v71
	v_lshlrev_b32_e32 v58, 16, v59
	v_and_b32_e32 v59, 0xffff0000, v59
	v_pk_mul_f32 v[58:59], v[58:59], v[70:71]
	v_pk_fma_f32 v[70:71], v[4:5], v[110:111], 0 op_sel_hi:[1,1,0]
	s_waitcnt vmcnt(10)
; __device__ __forceinline__ float fsigmoid(float v) { return __builtin_amdgcn_rcpf(1.f + __builtin_amdgcn_exp2f(-v * LOG2E)); }
; template <int NI> __device__ __forceinline__ void conv_items(bf16_t* PB, const float* cw, const int (&items)[NI], int lane) {
;     ...
;     for (int q = 0; q < NI; ++q) {
;         float y[8];
; #pragma unroll
;         for (int e = 0; e < 8; ++e) y[e] = 0.f;
; #pragma unroll
;         for (int dt = 0; dt < 3; ++dt) { float u[8], c[8]; unpack8(uw[q][dt], u); unpack8(cgw[q][dt], c); const float mk = (dt <= t[q]) ? 1.f : 0.f;
; #pragma unroll
;             for (int e = 0; e < 8; ++e) { const float wv = (e < 4) ? w0[q][dt][e & 3] : w1[q][dt][e & 3]; y[e] += (mk * wv) * (c[e] * u[e]); } }
;         float bg[8], zc[8]; unpack8(bgw[q], bg); unpack8(zcw[q], zc);
; #pragma unroll
;         for (int e = 0; e < 8; ++e) y[e] = bg[e] * y[e] * (zc[e] * fsigmoid(zc[e]));
	v_lshlrev_b32_e32 v110, 16, v72
	v_and_b32_e32 v111, 0xffff0000, v72
	v_lshlrev_b32_e32 v112, 16, v64
	v_and_b32_e32 v113, 0xffff0000, v64
	v_lshlrev_b32_e32 v72, 16, v73
	v_and_b32_e32 v73, 0xffff0000, v73
	v_lshlrev_b32_e32 v64, 16, v65
	v_and_b32_e32 v65, 0xffff0000, v65
	v_lshlrev_b32_e32 v118, 16, v74
	v_and_b32_e32 v119, 0xffff0000, v74
	v_lshlrev_b32_e32 v120, 16, v66
	v_and_b32_e32 v121, 0xffff0000, v66
	v_pk_fma_f32 v[56:57], v[6:7], v[56:57], 0 op_sel_hi:[1,1,0]
	v_pk_fma_f32 v[68:69], v[0:1], v[68:69], 0 op_sel_hi:[1,1,0]
	v_lshlrev_b32_e32 v74, 16, v75
	v_and_b32_e32 v75, 0xffff0000, v75
	v_lshlrev_b32_e32 v66, 16, v67
	v_and_b32_e32 v67, 0xffff0000, v67
	v_pk_mul_f32 v[110:111], v[112:113], v[110:111]
	v_pk_mul_f32 v[64:65], v[64:65], v[72:73]
	v_pk_mul_f32 v[72:73], v[120:121], v[118:119]
	v_pk_fma_f32 v[58:59], v[2:3], v[58:59], 0 op_sel_hi:[1,1,0]
	v_pk_mul_f32 v[66:67], v[66:67], v[74:75]
	v_add_f32_e32 v74, 1.0, v124
	v_pk_fma_f32 v[70:71], v[90:91], v[110:111], v[70:71]
	v_add_f32_e32 v75, 1.0, v127
	v_add_f32_e32 v90, 1.0, v128
	v_pk_fma_f32 v[56:57], v[106:107], v[64:65], v[56:57]
	v_add_f32_e32 v91, 1.0, v125
	v_add_f32_e32 v106, 1.0, v126
	v_pk_fma_f32 v[64:65], v[72:73], v[108:109], v[68:69]
	v_add_f32_e32 v108, 1.0, v129
	v_add_f32_e32 v109, 1.0, v130
	v_add_f32_e32 v110, 1.0, v131
	v_pk_fma_f32 v[58:59], v[66:67], v[84:85], v[58:59]
	v_rcp_f32_e32 v66, v74
	s_waitcnt vmcnt(9)
	v_lshlrev_b32_e32 v72, 16, v48
	v_and_b32_e32 v73, 0xffff0000, v48
	v_rcp_f32_e32 v67, v75
	v_rcp_f32_e32 v48, v90
	v_lshlrev_b32_e32 v74, 16, v49
	v_and_b32_e32 v75, 0xffff0000, v49
	v_rcp_f32_e32 v49, v91
	v_rcp_f32_e32 v84, v106
	v_rcp_f32_e32 v85, v108
	v_rcp_f32_e32 v109, v109
	v_rcp_f32_e32 v108, v110
	s_waitcnt vmcnt(8)
	v_lshlrev_b32_e32 v68, 16, v52
	v_and_b32_e32 v69, 0xffff0000, v52
	v_lshlrev_b32_e32 v52, 16, v53
	v_and_b32_e32 v53, 0xffff0000, v53
	v_lshlrev_b32_e32 v90, 16, v54
	v_and_b32_e32 v91, 0xffff0000, v54
	v_lshlrev_b32_e32 v106, 16, v50
	v_and_b32_e32 v107, 0xffff0000, v50
	v_lshlrev_b32_e32 v54, 16, v55
	v_and_b32_e32 v55, 0xffff0000, v55
	v_lshlrev_b32_e32 v50, 16, v51
	v_and_b32_e32 v51, 0xffff0000, v51
	v_pk_mul_f32 v[68:69], v[72:73], v[68:69]
	v_pk_mul_f32 v[52:53], v[74:75], v[52:53]
	v_pk_mul_f32 v[72:73], v[106:107], v[90:91]
	v_pk_mul_f32 v[50:51], v[50:51], v[54:55]
	v_and_b32_e32 v115, 0xffff0000, v60
	v_lshlrev_b32_e32 v60, 16, v61
	v_and_b32_e32 v61, 0xffff0000, v61
	v_lshlrev_b32_e32 v122, 16, v62
	v_and_b32_e32 v123, 0xffff0000, v62
	v_lshlrev_b32_e32 v62, 16, v63
	v_and_b32_e32 v63, 0xffff0000, v63
	v_pk_fma_f32 v[54:55], v[100:101], v[68:69], v[70:71]
	v_pk_fma_f32 v[52:53], v[102:103], v[52:53], v[56:57]
	v_pk_fma_f32 v[56:57], v[72:73], v[104:105], v[64:65]
	v_pk_fma_f32 v[50:51], v[50:51], v[86:87], v[58:59]
	v_pk_mul_f32 v[54:55], v[54:55], v[114:115]
	v_pk_mul_f32 v[52:53], v[52:53], v[60:61]
	v_pk_mul_f32 v[56:57], v[56:57], v[122:123]
	v_pk_mul_f32 v[50:51], v[50:51], v[62:63]
	s_waitcnt vmcnt(6)
	v_lshlrev_b32_e32 v58, 16, v44
	v_and_b32_e32 v59, 0xffff0000, v44
	v_lshlrev_b32_e32 v60, 16, v36
	v_and_b32_e32 v61, 0xffff0000, v36
	v_lshlrev_b32_e32 v44, 16, v45
	v_and_b32_e32 v45, 0xffff0000, v45
	v_lshlrev_b32_e32 v36, 16, v37
	v_and_b32_e32 v37, 0xffff0000, v37
	v_lshlrev_b32_e32 v64, 16, v46
	v_and_b32_e32 v65, 0xffff0000, v46
	v_lshlrev_b32_e32 v68, 16, v38
	v_and_b32_e32 v69, 0xffff0000, v38
	v_lshlrev_b32_e32 v46, 16, v47
	v_and_b32_e32 v47, 0xffff0000, v47
	v_lshlrev_b32_e32 v38, 16, v39
	v_and_b32_e32 v39, 0xffff0000, v39
	v_pk_mul_f32 v[66:67], v[66:67], v[88:89]
	v_pk_mul_f32 v[48:49], v[48:49], v[76:77]
	v_pk_mul_f32 v[72:73], v[84:85], v[116:117]
	v_pk_mul_f32 v[74:75], v[108:109], v[78:79]
	v_pk_mul_f32 v[36:37], v[36:37], v[44:45]
	v_pk_mul_f32 v[44:45], v[68:69], v[64:65]
	v_pk_mul_f32 v[38:39], v[38:39], v[46:47]
	v_pk_mul_f32 v[46:47], v[54:55], v[66:67]
	v_pk_mul_f32 v[48:49], v[52:53], v[48:49]
	v_pk_mul_f32 v[52:53], v[56:57], v[72:73]
	v_pk_mul_f32 v[50:51], v[50:51], v[74:75]
	v_pk_mul_f32 v[58:59], v[60:61], v[58:59]
	v_pk_fma_f32 v[6:7], v[6:7], v[36:37], 0 op_sel_hi:[1,1,0]
	v_pk_fma_f32 v[36:37], v[0:1], v[44:45], 0 op_sel_hi:[1,1,0]
	v_pk_fma_f32 v[38:39], v[2:3], v[38:39], 0 op_sel_hi:[1,1,0]
	v_cvt_pk_bf16_f32 v0, v46, v47
	v_cvt_pk_bf16_f32 v1, v48, v49
	v_cvt_pk_bf16_f32 v2, v52, v53
	v_cvt_pk_bf16_f32 v3, v50, v51
	s_waitcnt vmcnt(4)
; __device__ __forceinline__ float fsigmoid(float v) { return __builtin_amdgcn_rcpf(1.f + __builtin_amdgcn_exp2f(-v * LOG2E)); }
; __device__ __forceinline__ u32x4 pack8(const float (&f)[8]) { u32x4 w; w.x = cvtpk(f[0], f[1]); w.y = cvtpk(f[2], f[3]); w.z = cvtpk(f[4], f[5]); w.w = cvtpk(f[6], f[7]); return w; }
; template <int NI> __device__ __forceinline__ void conv_items(bf16_t* PB, const float* cw, const int (&items)[NI], int lane) {
;     ...
; #pragma unroll
;         for (int dt = 0; dt < 3; ++dt) { float u[8], c[8]; unpack8(uw[q][dt], u); unpack8(cgw[q][dt], c); const float mk = (dt <= t[q]) ? 1.f : 0.f;
; #pragma unroll
;             for (int e = 0; e < 8; ++e) { const float wv = (e < 4) ? w0[q][dt][e & 3] : w1[q][dt][e & 3]; y[e] += (mk * wv) * (c[e] * u[e]); } }
;         float bg[8], zc[8]; unpack8(bgw[q], bg); unpack8(zcw[q], zc);
; #pragma unroll
;         for (int e = 0; e < 8; ++e) y[e] = bg[e] * y[e] * (zc[e] * fsigmoid(zc[e]));
;         outw[q] = pack8(y); }
; #pragma unroll
;     for (int q = 0; q < NI; ++q) *(u32x4*)zp[q] = outw[q];
	v_lshlrev_b32_e32 v44, 16, v24
	v_and_b32_e32 v45, 0xffff0000, v24
	s_waitcnt vmcnt(3)
	v_lshlrev_b32_e32 v46, 16, v32
	v_and_b32_e32 v47, 0xffff0000, v32
	s_waitcnt vmcnt(2)
	v_lshlrev_b32_e32 v48, 16, v28
	v_and_b32_e32 v49, 0xffff0000, v28
	v_lshlrev_b32_e32 v24, 16, v25
	v_and_b32_e32 v25, 0xffff0000, v25
	v_lshlrev_b32_e32 v32, 16, v33
	v_and_b32_e32 v33, 0xffff0000, v33
	v_lshlrev_b32_e32 v28, 16, v29
	v_and_b32_e32 v29, 0xffff0000, v29
	v_lshlrev_b32_e32 v50, 16, v26
	v_and_b32_e32 v51, 0xffff0000, v26
	v_lshlrev_b32_e32 v52, 16, v34
	v_and_b32_e32 v53, 0xffff0000, v34
	v_lshlrev_b32_e32 v54, 16, v30
	v_and_b32_e32 v55, 0xffff0000, v30
	v_lshlrev_b32_e32 v26, 16, v27
	v_and_b32_e32 v27, 0xffff0000, v27
	v_lshlrev_b32_e32 v34, 16, v35
	v_and_b32_e32 v35, 0xffff0000, v35
	v_lshlrev_b32_e32 v30, 16, v31
	v_and_b32_e32 v31, 0xffff0000, v31
	v_pk_fma_f32 v[4:5], v[4:5], v[58:59], 0 op_sel_hi:[1,1,0]
	global_store_dwordx4 v[80:81], v[0:3], off offset:2048
	v_pk_mul_f32 v[26:27], v[34:35], v[26:27]
	v_mul_f32_e32 v34, 0xbfb8aa3b, v30
	v_pk_mul_f32 v[0:1], v[46:47], v[44:45]
	v_mul_f32_e32 v44, 0xbfb8aa3b, v48
	v_mul_f32_e32 v45, 0xbfb8aa3b, v49
	v_pk_mul_f32 v[2:3], v[32:33], v[24:25]
	v_mul_f32_e32 v32, 0xbfb8aa3b, v28
	v_mul_f32_e32 v33, 0xbfb8aa3b, v29
	v_pk_mul_f32 v[24:25], v[52:53], v[50:51]
	v_mul_f32_e32 v46, 0xbfb8aa3b, v54
	v_mul_f32_e32 v47, 0xbfb8aa3b, v55
	v_mul_f32_e32 v35, 0xbfb8aa3b, v31
	v_pk_fma_f32 v[0:1], v[12:13], v[0:1], v[4:5]
	v_exp_f32_e32 v44, v44
	v_exp_f32_e32 v45, v45
	v_pk_fma_f32 v[2:3], v[14:15], v[2:3], v[6:7]
	v_exp_f32_e32 v50, v32
	v_exp_f32_e32 v51, v33
	v_pk_fma_f32 v[4:5], v[8:9], v[24:25], v[36:37]
	v_exp_f32_e32 v36, v46
	v_exp_f32_e32 v37, v47
	v_pk_fma_f32 v[6:7], v[10:11], v[26:27], v[38:39]
	v_exp_f32_e32 v38, v34
	v_exp_f32_e32 v39, v35
	s_waitcnt vmcnt(1)
	v_lshlrev_b32_e32 v8, 16, v96
	v_and_b32_e32 v9, 0xffff0000, v96
	v_lshlrev_b32_e32 v10, 16, v92
	v_and_b32_e32 v11, 0xffff0000, v92
	v_lshlrev_b32_e32 v12, 16, v97
	v_and_b32_e32 v13, 0xffff0000, v97
	v_lshlrev_b32_e32 v14, 16, v93
	v_and_b32_e32 v15, 0xffff0000, v93
	v_lshlrev_b32_e32 v24, 16, v98
	v_and_b32_e32 v25, 0xffff0000, v98
	v_lshlrev_b32_e32 v26, 16, v94
	v_and_b32_e32 v27, 0xffff0000, v94
	v_lshlrev_b32_e32 v32, 16, v95
	v_and_b32_e32 v33, 0xffff0000, v95
	v_lshlrev_b32_e32 v34, 16, v99
	v_and_b32_e32 v35, 0xffff0000, v99
	v_pk_mul_f32 v[8:9], v[10:11], v[8:9]
	v_pk_mul_f32 v[10:11], v[14:15], v[12:13]
	v_pk_mul_f32 v[12:13], v[26:27], v[24:25]
	v_pk_mul_f32 v[14:15], v[32:33], v[34:35]
	v_pk_fma_f32 v[0:1], v[20:21], v[8:9], v[0:1]
	v_pk_fma_f32 v[2:3], v[22:23], v[10:11], v[2:3]
	v_pk_fma_f32 v[4:5], v[16:17], v[12:13], v[4:5]
	v_pk_fma_f32 v[6:7], v[18:19], v[14:15], v[6:7]
	v_add_f32_e32 v8, 1.0, v44
	v_add_f32_e32 v9, 1.0, v45
	v_add_f32_e32 v10, 1.0, v50
	v_add_f32_e32 v11, 1.0, v51
	v_add_f32_e32 v12, 1.0, v36
	v_add_f32_e32 v13, 1.0, v37
	v_add_f32_e32 v14, 1.0, v38
	v_add_f32_e32 v15, 1.0, v39
	v_rcp_f32_e32 v8, v8
	v_rcp_f32_e32 v9, v9
	v_rcp_f32_e32 v10, v10
	v_rcp_f32_e32 v11, v11
	v_rcp_f32_e32 v12, v12
	v_rcp_f32_e32 v13, v13
	v_rcp_f32_e32 v14, v14
	v_rcp_f32_e32 v15, v15
	v_lshlrev_b32_e32 v62, 16, v40
	v_and_b32_e32 v63, 0xffff0000, v40
	v_lshlrev_b32_e32 v40, 16, v41
	v_and_b32_e32 v41, 0xffff0000, v41
	v_lshlrev_b32_e32 v70, 16, v42
	v_and_b32_e32 v71, 0xffff0000, v42
	v_lshlrev_b32_e32 v42, 16, v43
	v_and_b32_e32 v43, 0xffff0000, v43
	v_pk_mul_f32 v[0:1], v[0:1], v[62:63]
	v_pk_mul_f32 v[2:3], v[2:3], v[40:41]
	v_pk_mul_f32 v[4:5], v[4:5], v[70:71]
	v_pk_mul_f32 v[6:7], v[6:7], v[42:43]
	v_pk_mul_f32 v[8:9], v[8:9], v[48:49]
	v_pk_mul_f32 v[10:11], v[10:11], v[28:29]
	v_pk_mul_f32 v[12:13], v[12:13], v[54:55]
	v_pk_mul_f32 v[14:15], v[14:15], v[30:31]
	s_add_i32 s76, s75, s74
	s_add_i32 s4, s88, s95
	v_pk_mul_f32 v[0:1], v[0:1], v[8:9]
	v_pk_mul_f32 v[2:3], v[2:3], v[10:11]
	v_pk_mul_f32 v[4:5], v[4:5], v[12:13]
	v_pk_mul_f32 v[6:7], v[6:7], v[14:15]
	s_cmpk_gt_i32 s4, 0x7fff
	v_cvt_pk_bf16_f32 v0, v0, v1
	v_cvt_pk_bf16_f32 v1, v2, v3
	v_cvt_pk_bf16_f32 v2, v4, v5
	v_cvt_pk_bf16_f32 v3, v6, v7
	global_store_dwordx4 v[82:83], v[0:3], off offset:2048
	s_cbranch_scc0 .LBB0_397
	s_add_i32 s75, s81, s95
